# attention main loop hand-scheduled for fixed-reference mode: counted lgkmcnt LDS prefetch, DMA and row-sum adds in MFMA shadow, 4 PV MFMAs deferred across the barrier; original loop kept as fallback
# speedup vs baseline: 1.0483x; 1.0483x over previous
; #define LAS __attribute__((address_space(3)))
; __device__ __forceinline__ void attn_unit(const Args& a, int l, int b, int h, int R0, bool special, LAS unsigned char* lds, float kb, int wv, bool pre, bool hasn, int nb, int nh, int nR0) {
;     ...
;     const bf16_t* Kh = Kb + (size_t)(b * NH + h) * LP * 96;
;     LAS unsigned char* KB0 = lds; LAS unsigned char* VB0 = lds + 4 * KBUF;
;     int kofs[2], vofs[2];
;     const int kp1 = (wave < 5) ? wave + 8 : wave, vp1 = (wave == 0) ? 8 : wave;
; #pragma unroll
;     for (int i = 0; i < 2; ++i) { const int ck = (i == 0 ? wave : kp1) * 64 + lane, rk = ck / 13, qk = ck - rk * 13; kofs[i] = rk * 96 + (qk < 12 ? qk : 11) * 8;
;         const int cv = (i == 0 ? wave : vp1) * 64 + lane, rv = cv / 9, qv = cv - rv * 9; vofs[i] = rv * MP + (qv < 8 ? qv : 7) * 8; }
;     const bf16_t* Vh = Vb + (size_t)(h * 64) * MP + (size_t)b * LP;
;     ...
;     const bool fixed = kb > 0.f;
;     float mref = fixed ? kb * qnorm : 0.f, lsum = 0.f; f32x16 o0 = {}, o1 = {}, pc0 = {}, pc1 = {}, negm;
; #pragma unroll
;     for (int r = 0; r < 16; ++r) negm[r] = -mref;
;     if (tw >= 1) {
;         ATT_QK(pc0, pc1, 1, negm);
.LBB0_57:
	s_and_b64 s[0:1], s[30:31], exec
	s_cselect_b32 s75, 3, 2
	v_readfirstlane_b32 s0, v70
	s_add_i32 s75, s75, s0
	v_add_u32_e32 v0, s78, v181
	v_mul_lo_u32 v2, v68, 13
	v_mul_u32_u24_e32 v26, 0x90, v69
	s_mov_b32 s76, 2
	s_cmp_lt_i32 s77, 3
	v_sub_u32_e32 v17, v0, v2
	s_cbranch_scc1 .LBB0_111
	s_add_i32 s0, s68, s67
	s_andn2_b32 s22, s22, 63
	s_lshl_b32 s78, s69, 10
	s_mul_hi_i32 s1, s0, 0x186000
	s_mul_i32 s0, s0, 0x186000
	v_min_i32_e32 v0, 11, v17
	v_readlane_b32 s84, v252, 2
	v_lshl_add_u32 v2, v0, 3, v185
	v_readlane_b32 s85, v252, 3
	s_add_u32 s0, s84, s0
	v_ashrrev_i32_e32 v3, 31, v2
	s_addc_u32 s1, s85, s1
	v_lshl_add_u64 v[18:19], v[2:3], 1, s[0:1]
	v_add_u32_e32 v0, s22, v181
	v_lshl_add_u32 v2, v64, 3, v64
	v_lshl_add_u64 v[20:21], v[168:169], 1, s[0:1]
	s_add_u32 s0, s34, s81
	v_sub_u32_e32 v0, v0, v2
	s_addc_u32 s1, 0, s35
	v_min_i32_e32 v0, 7, v0
	v_lshl_add_u32 v2, v0, 3, v65
	s_add_u32 s0, s84, s0
	v_ashrrev_i32_e32 v3, 31, v2
	s_addc_u32 s1, s85, s1
	v_lshl_add_u64 v[22:23], v[2:3], 1, s[0:1]
	v_add_u32_e32 v0, s82, v181
	v_lshl_add_u32 v2, v66, 3, v66
	v_sub_u32_e32 v0, v0, v2
	v_min_i32_e32 v0, 7, v0
	v_lshl_add_u32 v2, v0, 3, v67
	v_ashrrev_i32_e32 v3, 31, v2
	v_mov_b32_e32 v14, v1
	v_mov_b32_e32 v15, v1
	v_readlane_b32 s86, v252, 4
	v_readlane_b32 s87, v252, 5
	v_lshl_add_u64 v[24:25], v[2:3], 1, s[0:1]
	v_mov_b32_e32 v0, v1
	v_mov_b32_e32 v2, v1
	v_mov_b32_e32 v3, v1
	v_mov_b32_e32 v4, v1
	v_mov_b32_e32 v5, v1
	v_mov_b32_e32 v6, v1
	v_mov_b32_e32 v7, v1
	v_mov_b32_e32 v8, v1
	v_mov_b32_e32 v9, v1
	v_mov_b32_e32 v10, v1
	v_mov_b32_e32 v11, v1
	v_mov_b32_e32 v12, v1
	v_mov_b32_e32 v13, v1
	v_mov_b64_e32 v[62:63], v[14:15]
	v_mov_b64_e32 v[78:79], v[14:15]
	v_add_u32_e32 v28, 0, v187
	v_add_u32_e32 v29, 0x11860, v26
	s_mov_b32 s79, 3
	s_mov_b32 s80, 1
	v_add_u32_e32 v30, 0x11840, v26
	v_add_u32_e32 v31, 0x11820, v26
	v_add_u32_e32 v191, 0x12a00, v26
	v_add_u32_e32 v192, 0x11800, v26
	v_add_u32_e32 v193, 0x10660, v26
	v_add_u32_e32 v194, 0x10640, v26
	v_add_u32_e32 v195, 0x10620, v26
	v_add_u32_e32 v196, 0x10600, v26
	s_add_i32 s81, s66, 0x13c00
	s_add_i32 s82, s66, 0x16000
	s_mov_b32 s83, 0
	v_mov_b32_e32 v27, 0
	s_mov_b32 s87, 2
	s_movk_i32 s84, 0xff
	s_mov_b32 s85, 0x15c00
	s_mov_b32 s86, 4
	v_mov_b64_e32 v[60:61], v[12:13]
	v_mov_b64_e32 v[58:59], v[10:11]
	v_mov_b64_e32 v[56:57], v[8:9]
	v_mov_b64_e32 v[54:55], v[6:7]
	v_mov_b64_e32 v[52:53], v[4:5]
	v_mov_b64_e32 v[50:51], v[2:3]
	v_mov_b64_e32 v[48:49], v[0:1]
	v_mov_b64_e32 v[76:77], v[12:13]
	v_mov_b64_e32 v[74:75], v[10:11]
	v_mov_b64_e32 v[72:73], v[8:9]
	v_mov_b64_e32 v[70:71], v[6:7]
	v_mov_b64_e32 v[68:69], v[4:5]
	v_mov_b64_e32 v[66:67], v[2:3]
	v_mov_b64_e32 v[64:65], v[0:1]
	s_and_b64 vcc, exec, s[44:45]
	s_cbranch_vccnz .Lfa_entry

; __device__ __forceinline__ void attn_unit(const Args& a, int l, int b, int h, int R0, bool special, LAS unsigned char* lds, float kb, int wv, bool pre, bool hasn, int nb, int nh, int nR0) {
;     ...
;     if (wave >= 4) __builtin_amdgcn_s_setprio(1);
.Lfa_entry:
	v_mov_b32_e32 v210, 0
	v_mov_b32_e32 v211, 0
	v_mov_b32_e32 v212, 0
	v_mov_b32_e32 v213, 0
	v_mov_b32_e32 v214, 0
	v_mov_b32_e32 v215, 0
	v_mov_b32_e32 v216, 0
	v_mov_b32_e32 v217, 0
	v_mov_b32_e32 v218, 0
	v_mov_b32_e32 v219, 0
	v_mov_b32_e32 v220, 0
	v_mov_b32_e32 v221, 0
	v_mov_b32_e32 v222, 0
	v_mov_b32_e32 v223, 0
	v_mov_b32_e32 v224, 0
	v_mov_b32_e32 v225, 0
	v_mov_b32_e32 v234, 0
	v_mov_b32_e32 v235, 0
	v_mov_b32_e32 v236, 0
	v_mov_b32_e32 v237, 0
	v_mov_b32_e32 v238, 0
	v_mov_b32_e32 v239, 0
	v_mov_b32_e32 v240, 0
	v_mov_b32_e32 v241, 0
	v_mov_b32_e32 v247, 0
	v_mov_b32_e32 v248, 0
	v_mov_b32_e32 v249, 0
	v_mov_b32_e32 v250, 0
	s_mov_b32 s0, 0xd000
	v_add3_u32 v251, v26, v28, s0
	s_mov_b64 s[22:23], 0x220c000
	s_mov_b64 s[24:25], 0x220f000
	s_mov_b64 s[34:35], 0x1b900180
	s_mov_b64 s[48:49], 0x1b900200
	s_movk_i32 s30, 0x2400
	s_mov_b32 s31, 0
.Lfa_loop:
	s_add_i32 s76, s87, 2
	s_and_b32 s0, s87, 3
	s_mulk_i32 s0, 0x3400
	v_add_u32_e32 v230, s0, v190
	v_add_u32_e32 v231, s30, v251
	ds_read_b128 v[2:5], v230
	ds_read_b128 v[6:9], v230 offset:6656
	ds_read_b128 v[10:13], v230 offset:32
	ds_read_b128 v[198:201], v230 offset:6688
	ds_read_b128 v[202:205], v230 offset:64
	ds_read_b128 v[206:209], v230 offset:6720
	v_mfma_f32_32x32x16_bf16 v[64:79], v[210:213], v[234:237], v[64:79]
	v_exp_f32_e32 v96, v96
	v_exp_f32_e32 v97, v97
	v_add_f32_e32 v247, v247, v96
	v_exp_f32_e32 v98, v98
	v_mfma_f32_32x32x16_bf16 v[48:63], v[214:217], v[234:237], v[48:63]
	s_mov_b32 s96, 0
	s_cmp_gt_u32 s76, s73
	s_cbranch_scc1 .Lfa_a_nok
	s_add_i32 s1, s76, 0
	s_and_b32 s1, s1, 3
	s_mulk_i32 s1, 0x3400
	s_add_i32 m0, s1, s66
	v_lshl_add_u64 v[226:227], v[20:21], 0, s[22:23]
	s_mov_b32 s96, s75
	global_load_lds_dwordx4 v[226:227], off
	s_and_b64 vcc, exec, s[40:41]
	s_cbranch_vccnz .Lfa_a_nok
	s_add_i32 m0, s1, s78
	v_lshl_add_u64 v[226:227], v[18:19], 0, s[22:23]
	global_load_lds_dwordx4 v[226:227], off
.Lfa_a_nok:
	v_add_f32_e32 v248, v248, v97
	v_exp_f32_e32 v99, v99
	v_add_f32_e32 v249, v249, v98
	v_exp_f32_e32 v100, v100
	v_mfma_f32_32x32x16_bf16 v[64:79], v[218:221], v[238:241], v[64:79]
	ds_read_b128 v[210:213], v230 offset:96
	ds_read_b128 v[214:217], v230 offset:6752
	v_add_f32_e32 v250, v250, v99
	v_exp_f32_e32 v101, v101
	v_add_f32_e32 v247, v247, v100
	v_exp_f32_e32 v102, v102
	v_mfma_f32_32x32x16_bf16 v[48:63], v[222:225], v[238:241], v[48:63]
	ds_read_b128 v[218:221], v230 offset:128
	ds_read_b128 v[222:225], v230 offset:6784
	ds_read_b128 v[234:237], v230 offset:160
	ds_read_b128 v[238:241], v230 offset:6816
	s_add_i32 s1, s87, 1
	s_cmp_gt_u32 s1, s73
	s_cbranch_scc1 .Lfa_a_nov
	s_add_i32 s1, s31, s66
	s_add_i32 m0, s1, 0xd000
	v_lshl_add_u64 v[226:227], v[22:23], 0, s[34:35]
	global_load_lds_dwordx4 v[226:227], off
	s_and_b64 vcc, exec, s[42:43]
	s_cbranch_vccnz .Lfa_a_nov
	s_add_i32 m0, s31, 0xf000
	v_lshl_add_u64 v[226:227], v[24:25], 0, s[34:35]
	global_load_lds_dwordx4 v[226:227], off
.Lfa_a_nov:
	v_add_f32_e32 v248, v248, v101
	v_exp_f32_e32 v103, v103
	v_add_f32_e32 v249, v249, v102
	v_add_f32_e32 v250, v250, v103
	s_waitcnt lgkmcnt(11)
	v_mfma_f32_32x32x16_bf16 v[128:143], v[2:5], v[156:159], v[32:47]
	v_cvt_pk_bf16_f32 v96, v96, v97
	v_cvt_pk_bf16_f32 v97, v98, v99
	v_cvt_pk_bf16_f32 v98, v100, v101
	v_cvt_pk_bf16_f32 v99, v102, v103
	s_waitcnt lgkmcnt(10)
	v_mfma_f32_32x32x16_bf16 v[112:127], v[6:9], v[156:159], v[32:47]
	ds_read_b128 v[2:5], v231
	ds_read_b128 v[6:9], v231 offset:4608
	v_exp_f32_e32 v104, v104
	v_exp_f32_e32 v105, v105
	v_add_f32_e32 v247, v247, v104
	v_exp_f32_e32 v106, v106
	s_waitcnt lgkmcnt(11)
	v_mfma_f32_32x32x16_bf16 v[128:143], v[10:13], v[160:163], v[128:143]
	v_add_f32_e32 v248, v248, v105
	v_exp_f32_e32 v107, v107
	v_add_f32_e32 v249, v249, v106
	v_exp_f32_e32 v108, v108
	s_waitcnt lgkmcnt(10)
	v_mfma_f32_32x32x16_bf16 v[112:127], v[198:201], v[160:163], v[112:127]
	ds_read_b128 v[10:13], v231 offset:32
	ds_read_b128 v[198:201], v231 offset:4640
	v_add_f32_e32 v250, v250, v107
	v_exp_f32_e32 v109, v109
	v_add_f32_e32 v247, v247, v108
	v_exp_f32_e32 v110, v110
	s_waitcnt lgkmcnt(11)
	v_mfma_f32_32x32x16_bf16 v[128:143], v[202:205], v[164:167], v[128:143]
	v_add_f32_e32 v248, v248, v109
	v_exp_f32_e32 v111, v111
	v_add_f32_e32 v249, v249, v110
	v_add_f32_e32 v250, v250, v111
	s_waitcnt lgkmcnt(10)
	v_mfma_f32_32x32x16_bf16 v[112:127], v[206:209], v[164:167], v[112:127]
	v_cvt_pk_bf16_f32 v104, v104, v105
	v_cvt_pk_bf16_f32 v105, v106, v107
	v_cvt_pk_bf16_f32 v106, v108, v109
	v_cvt_pk_bf16_f32 v107, v110, v111
	s_waitcnt lgkmcnt(9)
	v_mfma_f32_32x32x16_bf16 v[128:143], v[210:213], v[144:147], v[128:143]
	v_exp_f32_e32 v80, v80
	v_exp_f32_e32 v81, v81
	v_add_f32_e32 v247, v247, v80
	v_exp_f32_e32 v82, v82
	s_waitcnt lgkmcnt(8)
	v_mfma_f32_32x32x16_bf16 v[112:127], v[214:217], v[144:147], v[112:127]
	ds_read_b128 v[210:213], v231 offset:64
	ds_read_b128 v[214:217], v231 offset:4672
	v_add_f32_e32 v248, v248, v81
	v_exp_f32_e32 v83, v83
	v_add_f32_e32 v249, v249, v82
	v_exp_f32_e32 v84, v84
	s_waitcnt lgkmcnt(9)
	v_mfma_f32_32x32x16_bf16 v[128:143], v[218:221], v[148:151], v[128:143]
	v_add_f32_e32 v250, v250, v83
	v_exp_f32_e32 v85, v85
	v_add_f32_e32 v247, v247, v84
	v_exp_f32_e32 v86, v86
	s_waitcnt lgkmcnt(8)
	v_mfma_f32_32x32x16_bf16 v[112:127], v[222:225], v[148:151], v[112:127]
	ds_read_b128 v[218:221], v231 offset:96
	ds_read_b128 v[222:225], v231 offset:4704
	v_add_f32_e32 v248, v248, v85
	v_exp_f32_e32 v87, v87
	v_add_f32_e32 v249, v249, v86
	v_add_f32_e32 v250, v250, v87
	s_waitcnt lgkmcnt(9)
	v_mfma_f32_32x32x16_bf16 v[128:143], v[234:237], v[152:155], v[128:143]
	v_exp_f32_e32 v88, v88
	v_exp_f32_e32 v89, v89
	v_add_f32_e32 v247, v247, v88
	v_exp_f32_e32 v90, v90
	s_waitcnt lgkmcnt(8)
	v_mfma_f32_32x32x16_bf16 v[112:127], v[238:241], v[152:155], v[112:127]
	v_add_f32_e32 v248, v248, v89
	v_exp_f32_e32 v91, v91
	v_add_f32_e32 v249, v249, v90
	v_exp_f32_e32 v92, v92
	s_waitcnt lgkmcnt(7)
	v_mfma_f32_32x32x16_bf16 v[64:79], v[2:5], v[96:99], v[64:79]
	v_add_f32_e32 v250, v250, v91
	v_exp_f32_e32 v93, v93
	v_add_f32_e32 v247, v247, v92
	v_exp_f32_e32 v94, v94
	s_waitcnt lgkmcnt(6)
	v_mfma_f32_32x32x16_bf16 v[48:63], v[6:9], v[96:99], v[48:63]
	v_add_f32_e32 v248, v248, v93
	v_exp_f32_e32 v95, v95
	v_add_f32_e32 v249, v249, v94
	v_add_f32_e32 v250, v250, v95
	s_waitcnt lgkmcnt(5)
	v_mfma_f32_32x32x16_bf16 v[64:79], v[10:13], v[104:107], v[64:79]
	v_cvt_pk_bf16_f32 v234, v80, v81
	v_cvt_pk_bf16_f32 v235, v82, v83
	v_cvt_pk_bf16_f32 v236, v84, v85
	v_cvt_pk_bf16_f32 v237, v86, v87
	s_waitcnt lgkmcnt(4)
	v_mfma_f32_32x32x16_bf16 v[48:63], v[198:201], v[104:107], v[48:63]
	v_cvt_pk_bf16_f32 v238, v88, v89
	v_cvt_pk_bf16_f32 v239, v90, v91
	v_cvt_pk_bf16_f32 v240, v92, v93
	v_cvt_pk_bf16_f32 v241, v94, v95
	s_mov_b32 s1, s30
	s_add_i32 s30, s30, 0x2400
	s_cmp_eq_u32 s30, 0x6c00
	s_cselect_b32 s30, 0, s30
	s_mov_b32 s31, s1
	s_sub_i32 s0, s84, 64
	s_cmp_le_i32 s0, s74
	s_cbranch_scc0 .Lfa_mask_a
.Lfa_mask_a_ret:
	s_cmp_eq_u32 s96, 3
	s_cbranch_scc1 .Lfa_a_w3
	s_cmp_eq_u32 s96, 4
	s_cbranch_scc1 .Lfa_a_w4
	s_cmp_eq_u32 s96, 2
	s_cbranch_scc1 .Lfa_a_w2
	s_waitcnt vmcnt(0)
	s_branch .Lfa_a_wj
.Lfa_a_w2:
	s_waitcnt vmcnt(2)
	s_branch .Lfa_a_wj
.Lfa_a_w3:
	s_waitcnt vmcnt(3)
	s_branch .Lfa_a_wj
.Lfa_a_w4:
	s_waitcnt vmcnt(4)
.Lfa_a_wj:
	s_waitcnt lgkmcnt(0)
	s_barrier
	s_add_i32 s0, s87, 1
	s_and_b32 s0, s0, 3
	s_mulk_i32 s0, 0x3400
	v_add_u32_e32 v230, s0, v190
	v_add_u32_e32 v231, s30, v251
	ds_read_b128 v[2:5], v230
	ds_read_b128 v[6:9], v230 offset:6656
	ds_read_b128 v[10:13], v230 offset:32
	ds_read_b128 v[198:201], v230 offset:6688
	ds_read_b128 v[202:205], v230 offset:64
	ds_read_b128 v[206:209], v230 offset:6720
	v_mfma_f32_32x32x16_bf16 v[64:79], v[210:213], v[234:237], v[64:79]
	v_exp_f32_e32 v128, v128
	v_exp_f32_e32 v129, v129
	v_add_f32_e32 v247, v247, v128
	v_exp_f32_e32 v130, v130
	v_mfma_f32_32x32x16_bf16 v[48:63], v[214:217], v[234:237], v[48:63]
	s_mov_b32 s96, 0
	s_add_i32 s1, s76, 1
	s_cmp_gt_u32 s1, s73
	s_cbranch_scc1 .Lfa_b_nok
	s_add_i32 s1, s87, -1
	s_and_b32 s1, s1, 3
	s_mulk_i32 s1, 0x3400
	s_add_i32 m0, s1, s66
	v_lshl_add_u64 v[226:227], v[20:21], 0, s[24:25]
	s_mov_b32 s96, s75
	global_load_lds_dwordx4 v[226:227], off
	s_and_b64 vcc, exec, s[40:41]
	s_cbranch_vccnz .Lfa_b_nok
	s_add_i32 m0, s1, s78
	v_lshl_add_u64 v[226:227], v[18:19], 0, s[24:25]
	global_load_lds_dwordx4 v[226:227], off
.Lfa_b_nok:
	v_add_f32_e32 v248, v248, v129
	v_exp_f32_e32 v131, v131
	v_add_f32_e32 v249, v249, v130
	v_exp_f32_e32 v132, v132
	v_mfma_f32_32x32x16_bf16 v[64:79], v[218:221], v[238:241], v[64:79]
	ds_read_b128 v[210:213], v230 offset:96
	ds_read_b128 v[214:217], v230 offset:6752
	v_add_f32_e32 v250, v250, v131
	v_exp_f32_e32 v133, v133
	v_add_f32_e32 v247, v247, v132
	v_exp_f32_e32 v134, v134
	v_mfma_f32_32x32x16_bf16 v[48:63], v[222:225], v[238:241], v[48:63]
	ds_read_b128 v[218:221], v230 offset:128
	ds_read_b128 v[222:225], v230 offset:6784
	ds_read_b128 v[234:237], v230 offset:160
	ds_read_b128 v[238:241], v230 offset:6816
	s_cmp_gt_u32 s76, s73
	s_cbranch_scc1 .Lfa_b_nov
	s_add_i32 s1, s31, s66
	s_add_i32 m0, s1, 0xd000
	v_lshl_add_u64 v[226:227], v[22:23], 0, s[48:49]
	global_load_lds_dwordx4 v[226:227], off
	s_and_b64 vcc, exec, s[42:43]
	s_cbranch_vccnz .Lfa_b_nov
	s_add_i32 m0, s31, 0xf000
	v_lshl_add_u64 v[226:227], v[24:25], 0, s[48:49]
	global_load_lds_dwordx4 v[226:227], off
.Lfa_b_nov:
	v_add_f32_e32 v248, v248, v133
	v_exp_f32_e32 v135, v135
	v_add_f32_e32 v249, v249, v134
	v_add_f32_e32 v250, v250, v135
	s_waitcnt lgkmcnt(11)
	v_mfma_f32_32x32x16_bf16 v[96:111], v[2:5], v[156:159], v[32:47]
	v_cvt_pk_bf16_f32 v128, v128, v129
	v_cvt_pk_bf16_f32 v129, v130, v131
	v_cvt_pk_bf16_f32 v130, v132, v133
	v_cvt_pk_bf16_f32 v131, v134, v135
	s_waitcnt lgkmcnt(10)
	v_mfma_f32_32x32x16_bf16 v[80:95], v[6:9], v[156:159], v[32:47]
	ds_read_b128 v[2:5], v231
	ds_read_b128 v[6:9], v231 offset:4608
	v_exp_f32_e32 v136, v136
	v_exp_f32_e32 v137, v137
	v_add_f32_e32 v247, v247, v136
	v_exp_f32_e32 v138, v138
	s_waitcnt lgkmcnt(11)
	v_mfma_f32_32x32x16_bf16 v[96:111], v[10:13], v[160:163], v[96:111]
	v_add_f32_e32 v248, v248, v137
	v_exp_f32_e32 v139, v139
	v_add_f32_e32 v249, v249, v138
	v_exp_f32_e32 v140, v140
	s_waitcnt lgkmcnt(10)
	v_mfma_f32_32x32x16_bf16 v[80:95], v[198:201], v[160:163], v[80:95]
	ds_read_b128 v[10:13], v231 offset:32
	ds_read_b128 v[198:201], v231 offset:4640
	v_add_f32_e32 v250, v250, v139
	v_exp_f32_e32 v141, v141
	v_add_f32_e32 v247, v247, v140
	v_exp_f32_e32 v142, v142
	s_waitcnt lgkmcnt(11)
	v_mfma_f32_32x32x16_bf16 v[96:111], v[202:205], v[164:167], v[96:111]
	v_add_f32_e32 v248, v248, v141
	v_exp_f32_e32 v143, v143
	v_add_f32_e32 v249, v249, v142
	v_add_f32_e32 v250, v250, v143
	s_waitcnt lgkmcnt(10)
	v_mfma_f32_32x32x16_bf16 v[80:95], v[206:209], v[164:167], v[80:95]
	v_cvt_pk_bf16_f32 v136, v136, v137
	v_cvt_pk_bf16_f32 v137, v138, v139
	v_cvt_pk_bf16_f32 v138, v140, v141
	v_cvt_pk_bf16_f32 v139, v142, v143
	s_waitcnt lgkmcnt(9)
	v_mfma_f32_32x32x16_bf16 v[96:111], v[210:213], v[144:147], v[96:111]
	v_exp_f32_e32 v112, v112
	v_exp_f32_e32 v113, v113
	v_add_f32_e32 v247, v247, v112
	v_exp_f32_e32 v114, v114
	s_waitcnt lgkmcnt(8)
	v_mfma_f32_32x32x16_bf16 v[80:95], v[214:217], v[144:147], v[80:95]
	ds_read_b128 v[210:213], v231 offset:64
	ds_read_b128 v[214:217], v231 offset:4672
	v_add_f32_e32 v248, v248, v113
	v_exp_f32_e32 v115, v115
	v_add_f32_e32 v249, v249, v114
	v_exp_f32_e32 v116, v116
	s_waitcnt lgkmcnt(9)
	v_mfma_f32_32x32x16_bf16 v[96:111], v[218:221], v[148:151], v[96:111]
	v_add_f32_e32 v250, v250, v115
	v_exp_f32_e32 v117, v117
	v_add_f32_e32 v247, v247, v116
	v_exp_f32_e32 v118, v118
	s_waitcnt lgkmcnt(8)
	v_mfma_f32_32x32x16_bf16 v[80:95], v[222:225], v[148:151], v[80:95]
	ds_read_b128 v[218:221], v231 offset:96
	ds_read_b128 v[222:225], v231 offset:4704
	v_add_f32_e32 v248, v248, v117
	v_exp_f32_e32 v119, v119
	v_add_f32_e32 v249, v249, v118
	v_add_f32_e32 v250, v250, v119
	s_waitcnt lgkmcnt(9)
	v_mfma_f32_32x32x16_bf16 v[96:111], v[234:237], v[152:155], v[96:111]
	v_exp_f32_e32 v120, v120
	v_exp_f32_e32 v121, v121
	v_add_f32_e32 v247, v247, v120
	v_exp_f32_e32 v122, v122
	s_waitcnt lgkmcnt(8)
	v_mfma_f32_32x32x16_bf16 v[80:95], v[238:241], v[152:155], v[80:95]
	v_add_f32_e32 v248, v248, v121
	v_exp_f32_e32 v123, v123
	v_add_f32_e32 v249, v249, v122
	v_exp_f32_e32 v124, v124
	s_waitcnt lgkmcnt(7)
	v_mfma_f32_32x32x16_bf16 v[64:79], v[2:5], v[128:131], v[64:79]
	v_add_f32_e32 v250, v250, v123
	v_exp_f32_e32 v125, v125
	v_add_f32_e32 v247, v247, v124
	v_exp_f32_e32 v126, v126
	s_waitcnt lgkmcnt(6)
	v_mfma_f32_32x32x16_bf16 v[48:63], v[6:9], v[128:131], v[48:63]
	v_add_f32_e32 v248, v248, v125
	v_exp_f32_e32 v127, v127
	v_add_f32_e32 v249, v249, v126
	v_add_f32_e32 v250, v250, v127
	s_waitcnt lgkmcnt(5)
	v_mfma_f32_32x32x16_bf16 v[64:79], v[10:13], v[136:139], v[64:79]
	v_cvt_pk_bf16_f32 v234, v112, v113
	v_cvt_pk_bf16_f32 v235, v114, v115
	v_cvt_pk_bf16_f32 v236, v116, v117
	v_cvt_pk_bf16_f32 v237, v118, v119
	s_waitcnt lgkmcnt(4)
	v_mfma_f32_32x32x16_bf16 v[48:63], v[198:201], v[136:139], v[48:63]
	v_cvt_pk_bf16_f32 v238, v120, v121
	v_cvt_pk_bf16_f32 v239, v122, v123
	v_cvt_pk_bf16_f32 v240, v124, v125
	v_cvt_pk_bf16_f32 v241, v126, v127
	s_mov_b32 s1, s30
	s_add_i32 s30, s30, 0x2400
	s_cmp_eq_u32 s30, 0x6c00
	s_cselect_b32 s30, 0, s30
	s_mov_b32 s31, s1
	s_cmp_le_i32 s84, s74
	s_cbranch_scc0 .Lfa_mask_b

; __device__ __forceinline__ float xor32f(float v) { const auto rr = __builtin_amdgcn_permlane32_swap(__float_as_uint(v), __float_as_uint(v), false, false); const unsigned me = __float_as_uint(v); return __uint_as_float(rr[0] == me ? rr[1] : rr[0]); }
; #define ATT_ISSUE(t) do { if ((t) + 3 <= TL) ATT_DMAK((t) + 3); if ((t) + 2 <= TL) ATT_DMAV((t) + 2); } while (0)
; #define ATT_SYNC(t) do { if ((t) + 3 <= TL) { if (nis == 4) asm volatile("s_waitcnt vmcnt(4)" ::: "memory"); else if (nis == 3) asm volatile("s_waitcnt vmcnt(3)" ::: "memory"); else asm volatile("s_waitcnt vmcnt(2)" ::: "memory"); } \
;         else asm volatile("s_waitcnt vmcnt(0)" ::: "memory"); \
;         LDS_WAIT(); __builtin_amdgcn_s_barrier(); asm volatile("" ::: "memory"); } while (0)
; #define ATT_TAIL(t, C0, C1) do { ATT_ISSUE(t); bf16x8 vf[8], pa[4]; ATT_LDV(t); ATT_EXPP(C0, C1); ATT_PV(); ATT_SYNC(t); } while (0)
; __device__ __forceinline__ void attn_unit(const Args& a, int l, int b, int h, int R0, bool special, LAS unsigned char* lds, float kb, int wv, bool pre, bool hasn, int nb, int nh, int nR0) {
;     ...
;         f32x16 pb0, pb1; int t = 1;
;         for (; t + 1 < tw; t += 2) { ATT_BODY(t, pc0, pc1, pb0, pb1); ATT_BODY(t + 1, pb0, pb1, pc0, pc1); }
;         if (t < tw) { ATT_BODY(t, pc0, pc1, pb0, pb1); ++t; ATT_TAIL(t, pb0, pb1); ++t; }
;         else if (t == tw) { ATT_TAIL(t, pc0, pc1); ++t; }
;         for (; t <= TL; ++t) { ATT_ISSUE(t); ATT_SYNC(t); }
;     }
;     __builtin_amdgcn_s_setprio(0);
;     ...
;     lsum += xor32f(lsum);
.Lfa_b_wj:
	s_waitcnt lgkmcnt(0)
	s_barrier
	s_mov_b64 s[0:1], 0x6000
	s_addk_i32 s83, 0x4800
	v_lshl_add_u64 v[18:19], v[18:19], 0, s[0:1]
	v_lshl_add_u64 v[20:21], v[20:21], 0, s[0:1]
	s_addk_i32 s84, 0x80
	s_mov_b64 s[0:1], 0x100
	s_addk_i32 s85, 0x4800
	s_add_i32 s79, s79, 2
	s_add_i32 s86, s86, 2
	s_add_i32 s80, s80, 2
	v_lshl_add_u64 v[22:23], v[22:23], 0, s[0:1]
	v_lshl_add_u64 v[24:25], v[24:25], 0, s[0:1]
	s_cmp_lt_i32 s76, s77
	s_cbranch_scc0 .Lfa_exit
	s_mov_b32 s87, s76
	s_branch .Lfa_loop
.Lfa_exit:
	v_mfma_f32_32x32x16_bf16 v[64:79], v[210:213], v[234:237], v[64:79]
	v_mfma_f32_32x32x16_bf16 v[48:63], v[214:217], v[234:237], v[48:63]
	v_mfma_f32_32x32x16_bf16 v[64:79], v[218:221], v[238:241], v[64:79]
	v_mfma_f32_32x32x16_bf16 v[48:63], v[222:225], v[238:241], v[48:63]
	v_add_f32_e32 v247, v247, v248
	v_add_f32_e32 v249, v249, v250
	v_add_f32_e32 v247, v247, v249
	v_add_f32_e32 v27, v27, v247
	s_nop 7
	s_nop 7
	s_branch .LBB0_112
.Lfa_mask_a:
	s_nop 7
	s_nop 7
	v_add_u32_e32 v244, s84, v188
	v_add_u32_e32 v246, 0xffffffa1, v244
	v_add_u32_e32 v245, 0xffffff81, v244
	v_cmp_le_i32_e32 vcc, v246, v177
	s_nop 1
	v_cndmask_b32_e32 v112, v16, v112, vcc
	v_cmp_lt_i32_e32 vcc, v245, v177
	s_nop 1
	v_cndmask_b32_e32 v129, v16, v129, vcc
	v_cmp_le_i32_e32 vcc, v245, v177
	v_add_u32_e32 v245, 0xffffffa2, v244
	s_nop 0
	v_cndmask_b32_e32 v128, v16, v128, vcc
	v_cmp_le_i32_e32 vcc, v245, v177
	v_add_u32_e32 v245, 0xffffff83, v244
	s_nop 0
	v_cndmask_b32_e32 v113, v16, v113, vcc
	v_cmp_le_i32_e32 vcc, v245, v177
	v_add_u32_e32 v245, 0xffffffa3, v244
	s_nop 0
	v_cndmask_b32_e32 v130, v16, v130, vcc
	v_cmp_le_i32_e32 vcc, v245, v177
	v_add_u32_e32 v245, 0xffffff84, v244
	s_nop 0
	v_cndmask_b32_e32 v114, v16, v114, vcc
	v_cmp_le_i32_e32 vcc, v245, v177
	v_add_u32_e32 v245, 0xffffffa4, v244
	s_nop 0
	v_cndmask_b32_e32 v131, v16, v131, vcc
	v_cmp_le_i32_e32 vcc, v245, v177
	v_add_u32_e32 v245, 0xffffff85, v244
	s_nop 0
	v_cndmask_b32_e32 v115, v16, v115, vcc
	v_cmp_le_i32_e32 vcc, v245, v177
	v_add_u32_e32 v245, 0xffffffa5, v244
	s_nop 0
	v_cndmask_b32_e32 v132, v16, v132, vcc
	v_cmp_le_i32_e32 vcc, v245, v177
	v_add_u32_e32 v245, 0xffffff86, v244
	s_nop 0
	v_cndmask_b32_e32 v116, v16, v116, vcc
	v_cmp_le_i32_e32 vcc, v245, v177
	v_add_u32_e32 v245, 0xffffffa6, v244
	s_nop 0
	v_cndmask_b32_e32 v133, v16, v133, vcc
	v_cmp_le_i32_e32 vcc, v245, v177
	v_add_u32_e32 v245, 0xffffff87, v244
	s_nop 0
	v_cndmask_b32_e32 v117, v16, v117, vcc
	v_cmp_le_i32_e32 vcc, v245, v177
	v_add_u32_e32 v245, 0xffffffa7, v244
	s_nop 0
	v_cndmask_b32_e32 v134, v16, v134, vcc
	v_cmp_le_i32_e32 vcc, v245, v177
	v_add_u32_e32 v245, 0xffffff88, v244
	s_nop 0
	v_cndmask_b32_e32 v118, v16, v118, vcc
	v_cmp_le_i32_e32 vcc, v245, v177
	v_add_u32_e32 v245, 0xffffffa8, v244
	s_nop 0
	v_cndmask_b32_e32 v135, v16, v135, vcc
	v_cmp_le_i32_e32 vcc, v245, v177
	v_add_u32_e32 v245, 0xffffff91, v244
	s_nop 0
	v_cndmask_b32_e32 v119, v16, v119, vcc
	v_cmp_le_i32_e32 vcc, v245, v177
	v_add_u32_e32 v245, 0xffffffb1, v244
	s_nop 0
	v_cndmask_b32_e32 v136, v16, v136, vcc
	v_cmp_le_i32_e32 vcc, v245, v177
	v_add_u32_e32 v245, 0xffffff92, v244
	s_nop 0
	v_cndmask_b32_e32 v120, v16, v120, vcc
	v_cmp_le_i32_e32 vcc, v245, v177
	v_add_u32_e32 v245, 0xffffffb2, v244
	s_nop 0
	v_cndmask_b32_e32 v137, v16, v137, vcc
	v_cmp_le_i32_e32 vcc, v245, v177
	v_add_u32_e32 v245, 0xffffff93, v244
	s_nop 0
	v_cndmask_b32_e32 v121, v16, v121, vcc
	v_cmp_le_i32_e32 vcc, v245, v177
	v_add_u32_e32 v245, 0xffffffb3, v244
	s_nop 0
	v_cndmask_b32_e32 v138, v16, v138, vcc
	v_cmp_le_i32_e32 vcc, v245, v177
	v_add_u32_e32 v245, 0xffffff94, v244
	s_nop 0
	v_cndmask_b32_e32 v122, v16, v122, vcc
	v_cmp_le_i32_e32 vcc, v245, v177
	v_add_u32_e32 v245, 0xffffffb4, v244
	s_nop 0
	v_cndmask_b32_e32 v139, v16, v139, vcc
	v_cmp_le_i32_e32 vcc, v245, v177
	v_add_u32_e32 v245, 0xffffff95, v244
	s_nop 0
	v_cndmask_b32_e32 v123, v16, v123, vcc
	v_cmp_le_i32_e32 vcc, v245, v177
	v_add_u32_e32 v245, 0xffffffb5, v244
	s_nop 0
	v_cndmask_b32_e32 v140, v16, v140, vcc
	v_cmp_le_i32_e32 vcc, v245, v177
	v_add_u32_e32 v245, 0xffffff96, v244
	s_nop 0
	v_cndmask_b32_e32 v124, v16, v124, vcc
	v_cmp_le_i32_e32 vcc, v245, v177
	v_add_u32_e32 v245, 0xffffffb6, v244
	s_nop 0
	v_cndmask_b32_e32 v141, v16, v141, vcc
	v_cmp_le_i32_e32 vcc, v245, v177
	v_add_u32_e32 v245, 0xffffff97, v244
	s_nop 0
	v_cndmask_b32_e32 v125, v16, v125, vcc
	v_cmp_le_i32_e32 vcc, v245, v177
	v_add_u32_e32 v245, 0xffffffb7, v244
	s_nop 0
	v_cndmask_b32_e32 v142, v16, v142, vcc
	v_cmp_le_i32_e32 vcc, v245, v177
	v_add_u32_e32 v245, 0xffffff98, v244
	s_nop 0
	v_cndmask_b32_e32 v126, v16, v126, vcc
	v_cmp_le_i32_e32 vcc, v245, v177
	v_add_u32_e32 v245, 0xffffffb8, v244
	s_nop 0
	v_cndmask_b32_e32 v143, v16, v143, vcc
	v_cmp_le_i32_e32 vcc, v245, v177
	s_nop 1
	v_cndmask_b32_e32 v127, v16, v127, vcc
	s_branch .Lfa_mask_a_ret
.Lfa_mask_b:
	s_nop 7
	s_nop 7
	v_add_u32_e32 v244, s84, v188
	v_subrev_u32_e32 v246, 31, v244
	v_subrev_u32_e32 v245, 63, v244
	v_cmp_le_i32_e32 vcc, v246, v177
	s_nop 1
	v_cndmask_b32_e32 v80, v16, v80, vcc
	v_cmp_lt_i32_e32 vcc, v245, v177
	s_nop 1
	v_cndmask_b32_e32 v97, v16, v97, vcc
	v_cmp_le_i32_e32 vcc, v245, v177
	v_subrev_u32_e32 v245, 30, v244
	s_nop 0
	v_cndmask_b32_e32 v96, v16, v96, vcc
	v_cmp_le_i32_e32 vcc, v245, v177
	v_subrev_u32_e32 v245, 61, v244
	s_nop 0
	v_cndmask_b32_e32 v81, v16, v81, vcc
	v_cmp_le_i32_e32 vcc, v245, v177
	v_subrev_u32_e32 v245, 29, v244
	s_nop 0
	v_cndmask_b32_e32 v98, v16, v98, vcc
	v_cmp_le_i32_e32 vcc, v245, v177
	v_subrev_u32_e32 v245, 60, v244
	s_nop 0
	v_cndmask_b32_e32 v82, v16, v82, vcc
	v_cmp_le_i32_e32 vcc, v245, v177
	v_subrev_u32_e32 v245, 28, v244
	s_nop 0
	v_cndmask_b32_e32 v99, v16, v99, vcc
	v_cmp_le_i32_e32 vcc, v245, v177
	v_subrev_u32_e32 v245, 59, v244
	s_nop 0
	v_cndmask_b32_e32 v83, v16, v83, vcc
	v_cmp_le_i32_e32 vcc, v245, v177
	v_subrev_u32_e32 v245, 27, v244
	s_nop 0
	v_cndmask_b32_e32 v100, v16, v100, vcc
	v_cmp_le_i32_e32 vcc, v245, v177
	v_subrev_u32_e32 v245, 58, v244
	s_nop 0
	v_cndmask_b32_e32 v84, v16, v84, vcc
	v_cmp_le_i32_e32 vcc, v245, v177
	v_subrev_u32_e32 v245, 26, v244
	s_nop 0
	v_cndmask_b32_e32 v101, v16, v101, vcc
	v_cmp_le_i32_e32 vcc, v245, v177
	v_subrev_u32_e32 v245, 57, v244
	s_nop 0
	v_cndmask_b32_e32 v85, v16, v85, vcc
	v_cmp_le_i32_e32 vcc, v245, v177
	v_subrev_u32_e32 v245, 25, v244
	s_nop 0
	v_cndmask_b32_e32 v102, v16, v102, vcc
	v_cmp_le_i32_e32 vcc, v245, v177
	v_subrev_u32_e32 v245, 56, v244
	s_nop 0
	v_cndmask_b32_e32 v86, v16, v86, vcc
	v_cmp_le_i32_e32 vcc, v245, v177
	v_subrev_u32_e32 v245, 24, v244
	s_nop 0
	v_cndmask_b32_e32 v103, v16, v103, vcc
	v_cmp_le_i32_e32 vcc, v245, v177
	v_subrev_u32_e32 v245, 47, v244
	s_nop 0
	v_cndmask_b32_e32 v87, v16, v87, vcc
	v_cmp_le_i32_e32 vcc, v245, v177
	v_add_u32_e32 v245, -15, v244
	s_nop 0
	v_cndmask_b32_e32 v104, v16, v104, vcc
	v_cmp_le_i32_e32 vcc, v245, v177
	v_subrev_u32_e32 v245, 46, v244
	s_nop 0
	v_cndmask_b32_e32 v88, v16, v88, vcc
	v_cmp_le_i32_e32 vcc, v245, v177
	v_add_u32_e32 v245, -14, v244
	s_nop 0
	v_cndmask_b32_e32 v105, v16, v105, vcc
	v_cmp_le_i32_e32 vcc, v245, v177
	v_subrev_u32_e32 v245, 45, v244
	s_nop 0
	v_cndmask_b32_e32 v89, v16, v89, vcc
	v_cmp_le_i32_e32 vcc, v245, v177
	v_add_u32_e32 v245, -13, v244
	s_nop 0
	v_cndmask_b32_e32 v106, v16, v106, vcc
	v_cmp_le_i32_e32 vcc, v245, v177
	v_subrev_u32_e32 v245, 44, v244
	s_nop 0
	v_cndmask_b32_e32 v90, v16, v90, vcc
	v_cmp_le_i32_e32 vcc, v245, v177
	v_add_u32_e32 v245, -12, v244
	s_nop 0
	v_cndmask_b32_e32 v107, v16, v107, vcc
	v_cmp_le_i32_e32 vcc, v245, v177
	v_subrev_u32_e32 v245, 43, v244
	s_nop 0
	v_cndmask_b32_e32 v91, v16, v91, vcc
	v_cmp_le_i32_e32 vcc, v245, v177
	v_add_u32_e32 v245, -11, v244
	s_nop 0
	v_cndmask_b32_e32 v108, v16, v108, vcc
	v_cmp_le_i32_e32 vcc, v245, v177
	v_subrev_u32_e32 v245, 42, v244
	s_nop 0
	v_cndmask_b32_e32 v92, v16, v92, vcc
	v_cmp_le_i32_e32 vcc, v245, v177
	v_add_u32_e32 v245, -10, v244
	s_nop 0
	v_cndmask_b32_e32 v109, v16, v109, vcc
	v_cmp_le_i32_e32 vcc, v245, v177
	v_subrev_u32_e32 v245, 41, v244
	s_nop 0
	v_cndmask_b32_e32 v93, v16, v93, vcc
	v_cmp_le_i32_e32 vcc, v245, v177
	v_add_u32_e32 v245, -9, v244
	s_nop 0
	v_cndmask_b32_e32 v110, v16, v110, vcc
	v_cmp_le_i32_e32 vcc, v245, v177
	v_subrev_u32_e32 v245, 40, v244
	v_add_u32_e32 v244, -8, v244
	v_cndmask_b32_e32 v94, v16, v94, vcc
	v_cmp_le_i32_e32 vcc, v245, v177
	s_nop 1
	v_cndmask_b32_e32 v111, v16, v111, vcc
	v_cmp_le_i32_e32 vcc, v244, v177
	s_nop 1
	v_cndmask_b32_e32 v95, v16, v95, vcc
	s_branch .Lfa_mask_b_ret
